# P8 k-loop: LDS-DMA loads take SGPR base + 32-bit VGPR offset; 16 per-iteration 64-bit VALU address adds removed (2 SALU pairs instead)
# speedup vs baseline: 1.0182x; 1.0029x over previous
.Lp8_nostage:
	ds_read_b128 v[130:133], v240
	ds_read_b128 v[134:137], v240 offset:1024
	ds_read_b128 v[138:141], v240 offset:2048
	ds_read_b128 v[142:145], v240 offset:3072
	s_add_u32 s50, s48, 0xfff80080
	s_addc_u32 s51, s49, -1
	s_cmp_eq_u32 s80, s87
	s_cselect_b32 s53, s41, s51
	s_cselect_b32 s52, s47, s50
	s_cselect_b32 s51, s39, s75
	s_cselect_b32 s50, s73, s74
	s_add_i32 m0, s21, 0xc000
	ds_read_b128 v[146:149], v241
	ds_read_b128 v[150:153], v241 offset:1024
	ds_read_b128 v[154:157], v241 offset:2048
	ds_read_b128 v[158:161], v241 offset:3072
	ds_read_b128 v[176:179], v241 offset:4096
	ds_read_b128 v[180:183], v241 offset:5120
	ds_read_b128 v[184:187], v241 offset:6144
	ds_read_b128 v[188:191], v241 offset:7168
	global_load_lds_dwordx4 v166, s[48:49]
	s_add_i32 m0, s21, 0xe000
	s_nop 0
	global_load_lds_dwordx4 v170, s[48:49]
	s_waitcnt lgkmcnt(8)
	s_barrier
	s_waitcnt lgkmcnt(0)
	s_setprio 1
	s_waitcnt lgkmcnt(0)
	v_mfma_f32_16x16x32_bf16 v[126:129], v[130:133], v[146:149], 0
	v_mfma_f32_16x16x32_bf16 v[122:125], v[138:141], v[146:149], 0
	v_mfma_f32_16x16x32_bf16 v[118:121], v[130:133], v[154:157], 0
	v_mfma_f32_16x16x32_bf16 v[114:117], v[138:141], v[154:157], 0
	v_mfma_f32_16x16x32_bf16 v[106:109], v[130:133], v[176:179], 0
	v_mfma_f32_16x16x32_bf16 v[98:101], v[138:141], v[176:179], 0
	v_mfma_f32_16x16x32_bf16 v[90:93], v[130:133], v[184:187], 0
	v_mfma_f32_16x16x32_bf16 v[82:85], v[138:141], v[184:187], 0
	v_mfma_f32_16x16x32_bf16 v[126:129], v[134:137], v[150:153], v[126:129]
	v_mfma_f32_16x16x32_bf16 v[122:125], v[142:145], v[150:153], v[122:125]
	v_mfma_f32_16x16x32_bf16 v[118:121], v[134:137], v[158:161], v[118:121]
	v_mfma_f32_16x16x32_bf16 v[114:117], v[142:145], v[158:161], v[114:117]
	v_mfma_f32_16x16x32_bf16 v[106:109], v[134:137], v[180:183], v[106:109]
	v_mfma_f32_16x16x32_bf16 v[98:101], v[142:145], v[180:183], v[98:101]
	v_mfma_f32_16x16x32_bf16 v[90:93], v[134:137], v[188:191], v[90:93]
	v_mfma_f32_16x16x32_bf16 v[82:85], v[142:145], v[188:191], v[82:85]
	s_setprio 0
	s_barrier
	s_add_i32 s81, s68, s56
	s_add_u32 s96, s50, 0x80
	s_addc_u32 s97, s51, 0
	s_mov_b32 m0, s81
	ds_read_b128 v[192:195], v242
	ds_read_b128 v[196:199], v242 offset:1024
	ds_read_b128 v[200:203], v242 offset:2048
	ds_read_b128 v[204:207], v242 offset:3072
	global_load_lds_dwordx4 v162, s[50:51]
	s_add_i32 m0, s81, 0x2000
	s_nop 0
	global_load_lds_dwordx4 v164, s[50:51]
	s_barrier
	s_waitcnt lgkmcnt(0)
	s_setprio 1
	s_waitcnt lgkmcnt(0)
	v_mfma_f32_16x16x32_bf16 v[110:113], v[192:195], v[146:149], 0
	v_mfma_f32_16x16x32_bf16 v[102:105], v[200:203], v[146:149], 0
	v_mfma_f32_16x16x32_bf16 v[94:97], v[192:195], v[154:157], 0
	v_mfma_f32_16x16x32_bf16 v[86:89], v[200:203], v[154:157], 0
	v_mfma_f32_16x16x32_bf16 v[78:81], v[192:195], v[176:179], 0
	v_mfma_f32_16x16x32_bf16 v[74:77], v[200:203], v[176:179], 0
	v_mfma_f32_16x16x32_bf16 v[70:73], v[192:195], v[184:187], 0
	v_mfma_f32_16x16x32_bf16 v[66:69], v[200:203], v[184:187], 0
	v_mfma_f32_16x16x32_bf16 v[110:113], v[196:199], v[150:153], v[110:113]
	v_mfma_f32_16x16x32_bf16 v[102:105], v[204:207], v[150:153], v[102:105]
	v_mfma_f32_16x16x32_bf16 v[94:97], v[196:199], v[158:161], v[94:97]
	v_mfma_f32_16x16x32_bf16 v[86:89], v[204:207], v[158:161], v[86:89]
	v_mfma_f32_16x16x32_bf16 v[78:81], v[196:199], v[180:183], v[78:81]
	v_mfma_f32_16x16x32_bf16 v[74:77], v[204:207], v[180:183], v[74:77]
	v_mfma_f32_16x16x32_bf16 v[70:73], v[196:199], v[188:191], v[70:73]
	v_mfma_f32_16x16x32_bf16 v[66:69], v[204:207], v[188:191], v[66:69]
	s_setprio 0
	s_mov_b32 m0, s21
	s_add_u32 s94, s52, 0x80
	s_addc_u32 s95, s53, 0
	s_barrier
	ds_read_b128 v[146:149], v241 offset:16384
	ds_read_b128 v[150:153], v241 offset:17408
	ds_read_b128 v[154:157], v241 offset:18432
	ds_read_b128 v[158:161], v241 offset:19456
	ds_read_b128 v[176:179], v241 offset:20480
	ds_read_b128 v[180:183], v241 offset:21504
	ds_read_b128 v[184:187], v241 offset:22528
	ds_read_b128 v[188:191], v241 offset:23552
	global_load_lds_dwordx4 v162, s[52:53]
	s_mov_b32 m0, s59
	s_nop 0
	global_load_lds_dwordx4 v164, s[52:53]
	s_barrier
	s_waitcnt lgkmcnt(0)
	s_setprio 1
	s_waitcnt lgkmcnt(0)
	v_mfma_f32_16x16x32_bf16 v[62:65], v[130:133], v[146:149], 0
	v_mfma_f32_16x16x32_bf16 v[58:61], v[138:141], v[146:149], 0
	v_mfma_f32_16x16x32_bf16 v[54:57], v[130:133], v[154:157], 0
	v_mfma_f32_16x16x32_bf16 v[50:53], v[138:141], v[154:157], 0
	v_mfma_f32_16x16x32_bf16 v[42:45], v[130:133], v[176:179], 0
	v_mfma_f32_16x16x32_bf16 v[34:37], v[138:141], v[176:179], 0
	v_mfma_f32_16x16x32_bf16 v[26:29], v[130:133], v[184:187], 0
	v_mfma_f32_16x16x32_bf16 v[18:21], v[138:141], v[184:187], 0
	v_mfma_f32_16x16x32_bf16 v[62:65], v[134:137], v[150:153], v[62:65]
	v_mfma_f32_16x16x32_bf16 v[58:61], v[142:145], v[150:153], v[58:61]
	v_mfma_f32_16x16x32_bf16 v[54:57], v[134:137], v[158:161], v[54:57]
	v_mfma_f32_16x16x32_bf16 v[50:53], v[142:145], v[158:161], v[50:53]
	v_mfma_f32_16x16x32_bf16 v[42:45], v[134:137], v[180:183], v[42:45]
	v_mfma_f32_16x16x32_bf16 v[34:37], v[142:145], v[180:183], v[34:37]
	v_mfma_f32_16x16x32_bf16 v[26:29], v[134:137], v[188:191], v[26:29]
	v_mfma_f32_16x16x32_bf16 v[18:21], v[142:145], v[188:191], v[18:21]
	s_setprio 0
	s_barrier
	s_add_u32 s82, s50, 0x80000
	s_addc_u32 s83, s51, 0
	s_add_i32 s81, s69, s56
	s_mov_b32 m0, s81
	s_nop 0
	global_load_lds_dwordx4 v162, s[82:83]
	s_add_i32 m0, s81, 0x2000
	s_nop 0
	global_load_lds_dwordx4 v164, s[82:83]
	s_waitcnt vmcnt(6)
	s_barrier
	s_setprio 1
	v_mfma_f32_16x16x32_bf16 v[46:49], v[192:195], v[146:149], 0
	v_mfma_f32_16x16x32_bf16 v[38:41], v[200:203], v[146:149], 0
	v_mfma_f32_16x16x32_bf16 v[30:33], v[192:195], v[154:157], 0
	v_mfma_f32_16x16x32_bf16 v[22:25], v[200:203], v[154:157], 0
	v_mfma_f32_16x16x32_bf16 v[14:17], v[192:195], v[176:179], 0
	v_mfma_f32_16x16x32_bf16 v[10:13], v[200:203], v[176:179], 0
	v_mfma_f32_16x16x32_bf16 v[6:9], v[192:195], v[184:187], 0
	v_mfma_f32_16x16x32_bf16 v[2:5], v[200:203], v[184:187], 0
	v_mfma_f32_16x16x32_bf16 v[46:49], v[196:199], v[150:153], v[46:49]
	v_mfma_f32_16x16x32_bf16 v[38:41], v[204:207], v[150:153], v[38:41]
	v_mfma_f32_16x16x32_bf16 v[30:33], v[196:199], v[158:161], v[30:33]
	v_mfma_f32_16x16x32_bf16 v[22:25], v[204:207], v[158:161], v[22:25]
	v_mfma_f32_16x16x32_bf16 v[14:17], v[196:199], v[180:183], v[14:17]
	v_mfma_f32_16x16x32_bf16 v[10:13], v[204:207], v[180:183], v[10:13]
	v_mfma_f32_16x16x32_bf16 v[6:9], v[196:199], v[188:191], v[6:9]
	v_mfma_f32_16x16x32_bf16 v[2:5], v[204:207], v[188:191], v[2:5]
	s_setprio 0
	s_add_i32 s81, 0, 0x18000
	v_add_u32_e32 v142, s81, v236
	s_barrier
	ds_read_b128 v[130:133], v142
	ds_read_b128 v[134:137], v142 offset:1024
	ds_read_b128 v[138:141], v142 offset:2048
	ds_read_b128 v[142:145], v142 offset:3072
	s_add_u32 s52, s52, 0x80000
	s_addc_u32 s53, s53, 0
	s_mov_b32 m0, s60
	ds_read_b128 v[146:149], v241 offset:32768
	ds_read_b128 v[150:153], v241 offset:33792
	ds_read_b128 v[154:157], v241 offset:34816
	ds_read_b128 v[158:161], v241 offset:35840
	ds_read_b128 v[176:179], v241 offset:36864
	ds_read_b128 v[180:183], v241 offset:37888
	ds_read_b128 v[184:187], v241 offset:38912
	ds_read_b128 v[188:191], v241 offset:39936
	global_load_lds_dwordx4 v162, s[52:53]
	s_mov_b32 m0, s61
	s_nop 0
	global_load_lds_dwordx4 v164, s[52:53]
	s_waitcnt lgkmcnt(8)
	s_barrier
	s_waitcnt lgkmcnt(0)
	s_setprio 1
	s_waitcnt lgkmcnt(0)
	v_mfma_f32_16x16x32_bf16 v[126:129], v[130:133], v[146:149], v[126:129]
	v_mfma_f32_16x16x32_bf16 v[122:125], v[138:141], v[146:149], v[122:125]
	v_mfma_f32_16x16x32_bf16 v[118:121], v[130:133], v[154:157], v[118:121]
	v_mfma_f32_16x16x32_bf16 v[114:117], v[138:141], v[154:157], v[114:117]
	v_mfma_f32_16x16x32_bf16 v[106:109], v[130:133], v[176:179], v[106:109]
	v_mfma_f32_16x16x32_bf16 v[98:101], v[138:141], v[176:179], v[98:101]
	v_mfma_f32_16x16x32_bf16 v[90:93], v[130:133], v[184:187], v[90:93]
	v_mfma_f32_16x16x32_bf16 v[82:85], v[138:141], v[184:187], v[82:85]
	v_mfma_f32_16x16x32_bf16 v[126:129], v[134:137], v[150:153], v[126:129]
	v_mfma_f32_16x16x32_bf16 v[122:125], v[142:145], v[150:153], v[122:125]
	v_mfma_f32_16x16x32_bf16 v[118:121], v[134:137], v[158:161], v[118:121]
	v_mfma_f32_16x16x32_bf16 v[114:117], v[142:145], v[158:161], v[114:117]
	v_mfma_f32_16x16x32_bf16 v[106:109], v[134:137], v[180:183], v[106:109]
	v_mfma_f32_16x16x32_bf16 v[98:101], v[142:145], v[180:183], v[98:101]
	v_mfma_f32_16x16x32_bf16 v[90:93], v[134:137], v[188:191], v[90:93]
	v_mfma_f32_16x16x32_bf16 v[82:85], v[142:145], v[188:191], v[82:85]
	s_setprio 0
	s_barrier
	s_add_i32 s52, 0, 0x1c000
	s_add_i32 s53, s81, s56
	v_add_u32_e32 v204, s52, v236
	s_mov_b32 m0, s53
	ds_read_b128 v[192:195], v204
	ds_read_b128 v[196:199], v204 offset:1024
	ds_read_b128 v[200:203], v204 offset:2048
	ds_read_b128 v[204:207], v204 offset:3072
	global_load_lds_dwordx4 v162, s[96:97]
	s_add_i32 m0, s53, 0x2000
	s_nop 0
	global_load_lds_dwordx4 v164, s[96:97]
	s_barrier
	s_waitcnt lgkmcnt(0)
	s_setprio 1
	s_waitcnt lgkmcnt(0)
	v_mfma_f32_16x16x32_bf16 v[110:113], v[192:195], v[146:149], v[110:113]
	v_mfma_f32_16x16x32_bf16 v[102:105], v[200:203], v[146:149], v[102:105]
	v_mfma_f32_16x16x32_bf16 v[94:97], v[192:195], v[154:157], v[94:97]
	v_mfma_f32_16x16x32_bf16 v[86:89], v[200:203], v[154:157], v[86:89]
	v_mfma_f32_16x16x32_bf16 v[78:81], v[192:195], v[176:179], v[78:81]
	v_mfma_f32_16x16x32_bf16 v[74:77], v[200:203], v[176:179], v[74:77]
	v_mfma_f32_16x16x32_bf16 v[70:73], v[192:195], v[184:187], v[70:73]
	v_mfma_f32_16x16x32_bf16 v[66:69], v[200:203], v[184:187], v[66:69]
	v_mfma_f32_16x16x32_bf16 v[110:113], v[196:199], v[150:153], v[110:113]
	v_mfma_f32_16x16x32_bf16 v[102:105], v[204:207], v[150:153], v[102:105]
	v_mfma_f32_16x16x32_bf16 v[94:97], v[196:199], v[158:161], v[94:97]
	v_mfma_f32_16x16x32_bf16 v[86:89], v[204:207], v[158:161], v[86:89]
	v_mfma_f32_16x16x32_bf16 v[78:81], v[196:199], v[180:183], v[78:81]
	v_mfma_f32_16x16x32_bf16 v[74:77], v[204:207], v[180:183], v[74:77]
	v_mfma_f32_16x16x32_bf16 v[70:73], v[196:199], v[188:191], v[70:73]
	v_mfma_f32_16x16x32_bf16 v[66:69], v[204:207], v[188:191], v[66:69]
	s_setprio 0
	s_mov_b32 m0, s64
	s_barrier
	ds_read_b128 v[146:149], v241 offset:49152
	ds_read_b128 v[150:153], v241 offset:50176
	ds_read_b128 v[154:157], v241 offset:51200
	ds_read_b128 v[158:161], v241 offset:52224
	ds_read_b128 v[176:179], v241 offset:53248
	ds_read_b128 v[180:183], v241 offset:54272
	ds_read_b128 v[184:187], v241 offset:55296
	ds_read_b128 v[188:191], v241 offset:56320
	global_load_lds_dwordx4 v162, s[94:95]
	s_mov_b32 m0, s65
	s_nop 0
	global_load_lds_dwordx4 v164, s[94:95]
	s_barrier
	s_waitcnt lgkmcnt(0)
	s_setprio 1
	s_waitcnt lgkmcnt(0)
	v_mfma_f32_16x16x32_bf16 v[62:65], v[130:133], v[146:149], v[62:65]
	v_mfma_f32_16x16x32_bf16 v[58:61], v[138:141], v[146:149], v[58:61]
	v_mfma_f32_16x16x32_bf16 v[54:57], v[130:133], v[154:157], v[54:57]
	v_mfma_f32_16x16x32_bf16 v[50:53], v[138:141], v[154:157], v[50:53]
	v_mfma_f32_16x16x32_bf16 v[42:45], v[130:133], v[176:179], v[42:45]
	v_mfma_f32_16x16x32_bf16 v[34:37], v[138:141], v[176:179], v[34:37]
	v_mfma_f32_16x16x32_bf16 v[26:29], v[130:133], v[184:187], v[26:29]
	v_mfma_f32_16x16x32_bf16 v[18:21], v[138:141], v[184:187], v[18:21]
	v_mfma_f32_16x16x32_bf16 v[62:65], v[134:137], v[150:153], v[62:65]
	v_mfma_f32_16x16x32_bf16 v[58:61], v[142:145], v[150:153], v[58:61]
	v_mfma_f32_16x16x32_bf16 v[54:57], v[134:137], v[158:161], v[54:57]
	v_mfma_f32_16x16x32_bf16 v[50:53], v[142:145], v[158:161], v[50:53]
	v_mfma_f32_16x16x32_bf16 v[42:45], v[134:137], v[180:183], v[42:45]
	v_mfma_f32_16x16x32_bf16 v[34:37], v[142:145], v[180:183], v[34:37]
	v_mfma_f32_16x16x32_bf16 v[26:29], v[134:137], v[188:191], v[26:29]
	v_mfma_f32_16x16x32_bf16 v[18:21], v[142:145], v[188:191], v[18:21]
	s_setprio 0
	s_barrier
	s_add_u32 s50, s50, 0x80080
	s_addc_u32 s51, s51, 0
	s_add_i32 s52, s52, s56
	s_mov_b32 m0, s52
	s_nop 0
	global_load_lds_dwordx4 v162, s[50:51]
	s_add_i32 m0, s52, 0x2000
	s_nop 0
	global_load_lds_dwordx4 v164, s[50:51]
	s_waitcnt vmcnt(6)
	s_barrier
	s_setprio 1
	v_mfma_f32_16x16x32_bf16 v[46:49], v[192:195], v[146:149], v[46:49]
	v_mfma_f32_16x16x32_bf16 v[38:41], v[200:203], v[146:149], v[38:41]
	v_mfma_f32_16x16x32_bf16 v[30:33], v[192:195], v[154:157], v[30:33]
	v_mfma_f32_16x16x32_bf16 v[22:25], v[200:203], v[154:157], v[22:25]
	v_mfma_f32_16x16x32_bf16 v[14:17], v[192:195], v[176:179], v[14:17]
	v_mfma_f32_16x16x32_bf16 v[10:13], v[200:203], v[176:179], v[10:13]
	v_mfma_f32_16x16x32_bf16 v[6:9], v[192:195], v[184:187], v[6:9]
	v_mfma_f32_16x16x32_bf16 v[2:5], v[200:203], v[184:187], v[2:5]
	v_mfma_f32_16x16x32_bf16 v[46:49], v[196:199], v[150:153], v[46:49]
	v_mfma_f32_16x16x32_bf16 v[38:41], v[204:207], v[150:153], v[38:41]
	v_mfma_f32_16x16x32_bf16 v[30:33], v[196:199], v[158:161], v[30:33]
	v_mfma_f32_16x16x32_bf16 v[22:25], v[204:207], v[158:161], v[22:25]
	v_mfma_f32_16x16x32_bf16 v[14:17], v[196:199], v[180:183], v[14:17]
	v_mfma_f32_16x16x32_bf16 v[10:13], v[204:207], v[180:183], v[10:13]
	v_mfma_f32_16x16x32_bf16 v[6:9], v[196:199], v[188:191], v[6:9]
	v_mfma_f32_16x16x32_bf16 v[2:5], v[204:207], v[188:191], v[2:5]
	s_setprio 0
	s_add_i32 s80, s80, 2
	s_add_u32 s48, s48, 0x100
	s_addc_u32 s49, s49, 0
	s_add_u32 s74, s74, 0x100
	s_addc_u32 s75, s75, 0
	s_cmp_gt_u32 s80, s87
	s_barrier
	s_cbranch_scc0 .LBB0_1098
	s_branch .Lp8_loop_exit
.LBB0_1098:
	ds_read_b128 v[130:133], v240
	ds_read_b128 v[134:137], v240 offset:1024
	ds_read_b128 v[138:141], v240 offset:2048
	ds_read_b128 v[142:145], v240 offset:3072
	s_add_u32 s50, s48, 0xfff80080
	s_addc_u32 s51, s49, -1
	s_cmp_eq_u32 s80, s87
	s_cselect_b32 s53, s41, s51
	s_cselect_b32 s52, s47, s50
	s_cselect_b32 s51, s39, s75
	s_cselect_b32 s50, s73, s74
	s_add_i32 m0, s21, 0xc000
	ds_read_b128 v[146:149], v241
	ds_read_b128 v[150:153], v241 offset:1024
	ds_read_b128 v[154:157], v241 offset:2048
	ds_read_b128 v[158:161], v241 offset:3072
	ds_read_b128 v[176:179], v241 offset:4096
	ds_read_b128 v[180:183], v241 offset:5120
	ds_read_b128 v[184:187], v241 offset:6144
	ds_read_b128 v[188:191], v241 offset:7168
	global_load_lds_dwordx4 v166, s[48:49]
	s_add_i32 m0, s21, 0xe000
	s_nop 0
	global_load_lds_dwordx4 v170, s[48:49]
	s_waitcnt lgkmcnt(8)
	s_barrier
	s_waitcnt lgkmcnt(0)
	s_setprio 1
	s_waitcnt lgkmcnt(0)
	v_mfma_f32_16x16x32_bf16 v[126:129], v[130:133], v[146:149], v[126:129]
	v_mfma_f32_16x16x32_bf16 v[122:125], v[138:141], v[146:149], v[122:125]
	v_mfma_f32_16x16x32_bf16 v[118:121], v[130:133], v[154:157], v[118:121]
	v_mfma_f32_16x16x32_bf16 v[114:117], v[138:141], v[154:157], v[114:117]
	v_mfma_f32_16x16x32_bf16 v[106:109], v[130:133], v[176:179], v[106:109]
	v_mfma_f32_16x16x32_bf16 v[98:101], v[138:141], v[176:179], v[98:101]
	v_mfma_f32_16x16x32_bf16 v[90:93], v[130:133], v[184:187], v[90:93]
	v_mfma_f32_16x16x32_bf16 v[82:85], v[138:141], v[184:187], v[82:85]
	v_mfma_f32_16x16x32_bf16 v[126:129], v[134:137], v[150:153], v[126:129]
	v_mfma_f32_16x16x32_bf16 v[122:125], v[142:145], v[150:153], v[122:125]
	v_mfma_f32_16x16x32_bf16 v[118:121], v[134:137], v[158:161], v[118:121]
	v_mfma_f32_16x16x32_bf16 v[114:117], v[142:145], v[158:161], v[114:117]
	v_mfma_f32_16x16x32_bf16 v[106:109], v[134:137], v[180:183], v[106:109]
	v_mfma_f32_16x16x32_bf16 v[98:101], v[142:145], v[180:183], v[98:101]
	v_mfma_f32_16x16x32_bf16 v[90:93], v[134:137], v[188:191], v[90:93]
	v_mfma_f32_16x16x32_bf16 v[82:85], v[142:145], v[188:191], v[82:85]
	s_setprio 0
	s_barrier
	s_add_i32 s81, s68, s56
	s_add_u32 s96, s50, 0x80
	s_addc_u32 s97, s51, 0
	s_mov_b32 m0, s81
	ds_read_b128 v[192:195], v242
	ds_read_b128 v[196:199], v242 offset:1024
	ds_read_b128 v[200:203], v242 offset:2048
	ds_read_b128 v[204:207], v242 offset:3072
	global_load_lds_dwordx4 v162, s[50:51]
	s_add_i32 m0, s81, 0x2000
	s_nop 0
	global_load_lds_dwordx4 v164, s[50:51]
	s_barrier
	s_waitcnt lgkmcnt(0)
	s_setprio 1
	s_waitcnt lgkmcnt(0)
	v_mfma_f32_16x16x32_bf16 v[110:113], v[192:195], v[146:149], v[110:113]
	v_mfma_f32_16x16x32_bf16 v[102:105], v[200:203], v[146:149], v[102:105]
	v_mfma_f32_16x16x32_bf16 v[94:97], v[192:195], v[154:157], v[94:97]
	v_mfma_f32_16x16x32_bf16 v[86:89], v[200:203], v[154:157], v[86:89]
	v_mfma_f32_16x16x32_bf16 v[78:81], v[192:195], v[176:179], v[78:81]
	v_mfma_f32_16x16x32_bf16 v[74:77], v[200:203], v[176:179], v[74:77]
	v_mfma_f32_16x16x32_bf16 v[70:73], v[192:195], v[184:187], v[70:73]
	v_mfma_f32_16x16x32_bf16 v[66:69], v[200:203], v[184:187], v[66:69]
	v_mfma_f32_16x16x32_bf16 v[110:113], v[196:199], v[150:153], v[110:113]
	v_mfma_f32_16x16x32_bf16 v[102:105], v[204:207], v[150:153], v[102:105]
	v_mfma_f32_16x16x32_bf16 v[94:97], v[196:199], v[158:161], v[94:97]
	v_mfma_f32_16x16x32_bf16 v[86:89], v[204:207], v[158:161], v[86:89]
	v_mfma_f32_16x16x32_bf16 v[78:81], v[196:199], v[180:183], v[78:81]
	v_mfma_f32_16x16x32_bf16 v[74:77], v[204:207], v[180:183], v[74:77]
	v_mfma_f32_16x16x32_bf16 v[70:73], v[196:199], v[188:191], v[70:73]
	v_mfma_f32_16x16x32_bf16 v[66:69], v[204:207], v[188:191], v[66:69]
	s_setprio 0
	s_mov_b32 m0, s21
	s_add_u32 s94, s52, 0x80
	s_addc_u32 s95, s53, 0
	s_barrier
	ds_read_b128 v[146:149], v241 offset:16384
	ds_read_b128 v[150:153], v241 offset:17408
	ds_read_b128 v[154:157], v241 offset:18432
	ds_read_b128 v[158:161], v241 offset:19456
	ds_read_b128 v[176:179], v241 offset:20480
	ds_read_b128 v[180:183], v241 offset:21504
	ds_read_b128 v[184:187], v241 offset:22528
	ds_read_b128 v[188:191], v241 offset:23552
	global_load_lds_dwordx4 v162, s[52:53]
	s_mov_b32 m0, s59
	s_nop 0
	global_load_lds_dwordx4 v164, s[52:53]
	s_barrier
	s_waitcnt lgkmcnt(0)
	s_setprio 1
	s_waitcnt lgkmcnt(0)
	v_mfma_f32_16x16x32_bf16 v[62:65], v[130:133], v[146:149], v[62:65]
	v_mfma_f32_16x16x32_bf16 v[58:61], v[138:141], v[146:149], v[58:61]
	v_mfma_f32_16x16x32_bf16 v[54:57], v[130:133], v[154:157], v[54:57]
	v_mfma_f32_16x16x32_bf16 v[50:53], v[138:141], v[154:157], v[50:53]
	v_mfma_f32_16x16x32_bf16 v[42:45], v[130:133], v[176:179], v[42:45]
	v_mfma_f32_16x16x32_bf16 v[34:37], v[138:141], v[176:179], v[34:37]
	v_mfma_f32_16x16x32_bf16 v[26:29], v[130:133], v[184:187], v[26:29]
	v_mfma_f32_16x16x32_bf16 v[18:21], v[138:141], v[184:187], v[18:21]
	v_mfma_f32_16x16x32_bf16 v[62:65], v[134:137], v[150:153], v[62:65]
	v_mfma_f32_16x16x32_bf16 v[58:61], v[142:145], v[150:153], v[58:61]
	v_mfma_f32_16x16x32_bf16 v[54:57], v[134:137], v[158:161], v[54:57]
	v_mfma_f32_16x16x32_bf16 v[50:53], v[142:145], v[158:161], v[50:53]
	v_mfma_f32_16x16x32_bf16 v[42:45], v[134:137], v[180:183], v[42:45]
	v_mfma_f32_16x16x32_bf16 v[34:37], v[142:145], v[180:183], v[34:37]
	v_mfma_f32_16x16x32_bf16 v[26:29], v[134:137], v[188:191], v[26:29]
	v_mfma_f32_16x16x32_bf16 v[18:21], v[142:145], v[188:191], v[18:21]
	s_setprio 0
	s_barrier
	s_add_u32 s82, s50, 0x80000
	s_addc_u32 s83, s51, 0
	s_add_i32 s81, s69, s56
	s_mov_b32 m0, s81
	s_nop 0
	global_load_lds_dwordx4 v162, s[82:83]
	s_add_i32 m0, s81, 0x2000
	s_nop 0
	global_load_lds_dwordx4 v164, s[82:83]
	s_waitcnt vmcnt(6)
	s_barrier
	s_setprio 1
	v_mfma_f32_16x16x32_bf16 v[46:49], v[192:195], v[146:149], v[46:49]
	v_mfma_f32_16x16x32_bf16 v[38:41], v[200:203], v[146:149], v[38:41]
	v_mfma_f32_16x16x32_bf16 v[30:33], v[192:195], v[154:157], v[30:33]
	v_mfma_f32_16x16x32_bf16 v[22:25], v[200:203], v[154:157], v[22:25]
	v_mfma_f32_16x16x32_bf16 v[14:17], v[192:195], v[176:179], v[14:17]
	v_mfma_f32_16x16x32_bf16 v[10:13], v[200:203], v[176:179], v[10:13]
	v_mfma_f32_16x16x32_bf16 v[6:9], v[192:195], v[184:187], v[6:9]
	v_mfma_f32_16x16x32_bf16 v[2:5], v[200:203], v[184:187], v[2:5]
	v_mfma_f32_16x16x32_bf16 v[46:49], v[196:199], v[150:153], v[46:49]
	v_mfma_f32_16x16x32_bf16 v[38:41], v[204:207], v[150:153], v[38:41]
	v_mfma_f32_16x16x32_bf16 v[30:33], v[196:199], v[158:161], v[30:33]
	v_mfma_f32_16x16x32_bf16 v[22:25], v[204:207], v[158:161], v[22:25]
	v_mfma_f32_16x16x32_bf16 v[14:17], v[196:199], v[180:183], v[14:17]
	v_mfma_f32_16x16x32_bf16 v[10:13], v[204:207], v[180:183], v[10:13]
	v_mfma_f32_16x16x32_bf16 v[6:9], v[196:199], v[188:191], v[6:9]
	v_mfma_f32_16x16x32_bf16 v[2:5], v[204:207], v[188:191], v[2:5]
	s_setprio 0
	s_add_i32 s81, 0, 0x18000
	v_add_u32_e32 v142, s81, v236
	s_barrier
	ds_read_b128 v[130:133], v142
	ds_read_b128 v[134:137], v142 offset:1024
	ds_read_b128 v[138:141], v142 offset:2048
	ds_read_b128 v[142:145], v142 offset:3072
	s_add_u32 s52, s52, 0x80000
	s_addc_u32 s53, s53, 0
	s_mov_b32 m0, s60
	ds_read_b128 v[146:149], v241 offset:32768
	ds_read_b128 v[150:153], v241 offset:33792
	ds_read_b128 v[154:157], v241 offset:34816
	ds_read_b128 v[158:161], v241 offset:35840
	ds_read_b128 v[176:179], v241 offset:36864
	ds_read_b128 v[180:183], v241 offset:37888
	ds_read_b128 v[184:187], v241 offset:38912
	ds_read_b128 v[188:191], v241 offset:39936
	global_load_lds_dwordx4 v162, s[52:53]
	s_mov_b32 m0, s61
	s_nop 0
	global_load_lds_dwordx4 v164, s[52:53]
	s_waitcnt lgkmcnt(8)
	s_barrier
	s_waitcnt lgkmcnt(0)
	s_setprio 1
	s_waitcnt lgkmcnt(0)
	v_mfma_f32_16x16x32_bf16 v[126:129], v[130:133], v[146:149], v[126:129]
	v_mfma_f32_16x16x32_bf16 v[122:125], v[138:141], v[146:149], v[122:125]
	v_mfma_f32_16x16x32_bf16 v[118:121], v[130:133], v[154:157], v[118:121]
	v_mfma_f32_16x16x32_bf16 v[114:117], v[138:141], v[154:157], v[114:117]
	v_mfma_f32_16x16x32_bf16 v[106:109], v[130:133], v[176:179], v[106:109]
	v_mfma_f32_16x16x32_bf16 v[98:101], v[138:141], v[176:179], v[98:101]
	v_mfma_f32_16x16x32_bf16 v[90:93], v[130:133], v[184:187], v[90:93]
	v_mfma_f32_16x16x32_bf16 v[82:85], v[138:141], v[184:187], v[82:85]
	v_mfma_f32_16x16x32_bf16 v[126:129], v[134:137], v[150:153], v[126:129]
	v_mfma_f32_16x16x32_bf16 v[122:125], v[142:145], v[150:153], v[122:125]
	v_mfma_f32_16x16x32_bf16 v[118:121], v[134:137], v[158:161], v[118:121]
	v_mfma_f32_16x16x32_bf16 v[114:117], v[142:145], v[158:161], v[114:117]
	v_mfma_f32_16x16x32_bf16 v[106:109], v[134:137], v[180:183], v[106:109]
	v_mfma_f32_16x16x32_bf16 v[98:101], v[142:145], v[180:183], v[98:101]
	v_mfma_f32_16x16x32_bf16 v[90:93], v[134:137], v[188:191], v[90:93]
	v_mfma_f32_16x16x32_bf16 v[82:85], v[142:145], v[188:191], v[82:85]
	s_setprio 0
	s_barrier
	s_add_i32 s52, 0, 0x1c000
	s_add_i32 s53, s81, s56
	v_add_u32_e32 v204, s52, v236
	s_mov_b32 m0, s53
	ds_read_b128 v[192:195], v204
	ds_read_b128 v[196:199], v204 offset:1024
	ds_read_b128 v[200:203], v204 offset:2048
	ds_read_b128 v[204:207], v204 offset:3072
	global_load_lds_dwordx4 v162, s[96:97]
	s_add_i32 m0, s53, 0x2000
	s_nop 0
	global_load_lds_dwordx4 v164, s[96:97]
	s_barrier
	s_waitcnt lgkmcnt(0)
	s_setprio 1
	s_waitcnt lgkmcnt(0)
	v_mfma_f32_16x16x32_bf16 v[110:113], v[192:195], v[146:149], v[110:113]
	v_mfma_f32_16x16x32_bf16 v[102:105], v[200:203], v[146:149], v[102:105]
	v_mfma_f32_16x16x32_bf16 v[94:97], v[192:195], v[154:157], v[94:97]
	v_mfma_f32_16x16x32_bf16 v[86:89], v[200:203], v[154:157], v[86:89]
	v_mfma_f32_16x16x32_bf16 v[78:81], v[192:195], v[176:179], v[78:81]
	v_mfma_f32_16x16x32_bf16 v[74:77], v[200:203], v[176:179], v[74:77]
	v_mfma_f32_16x16x32_bf16 v[70:73], v[192:195], v[184:187], v[70:73]
	v_mfma_f32_16x16x32_bf16 v[66:69], v[200:203], v[184:187], v[66:69]
	v_mfma_f32_16x16x32_bf16 v[110:113], v[196:199], v[150:153], v[110:113]
	v_mfma_f32_16x16x32_bf16 v[102:105], v[204:207], v[150:153], v[102:105]
	v_mfma_f32_16x16x32_bf16 v[94:97], v[196:199], v[158:161], v[94:97]
	v_mfma_f32_16x16x32_bf16 v[86:89], v[204:207], v[158:161], v[86:89]
	v_mfma_f32_16x16x32_bf16 v[78:81], v[196:199], v[180:183], v[78:81]
	v_mfma_f32_16x16x32_bf16 v[74:77], v[204:207], v[180:183], v[74:77]
	v_mfma_f32_16x16x32_bf16 v[70:73], v[196:199], v[188:191], v[70:73]
	v_mfma_f32_16x16x32_bf16 v[66:69], v[204:207], v[188:191], v[66:69]
	s_setprio 0
	s_mov_b32 m0, s64
	s_barrier
	ds_read_b128 v[146:149], v241 offset:49152
	ds_read_b128 v[150:153], v241 offset:50176
	ds_read_b128 v[154:157], v241 offset:51200
	ds_read_b128 v[158:161], v241 offset:52224
	ds_read_b128 v[176:179], v241 offset:53248
	ds_read_b128 v[180:183], v241 offset:54272
	ds_read_b128 v[184:187], v241 offset:55296
	ds_read_b128 v[188:191], v241 offset:56320
	global_load_lds_dwordx4 v162, s[94:95]
	s_mov_b32 m0, s65
	s_nop 0
	global_load_lds_dwordx4 v164, s[94:95]
	s_barrier
	s_waitcnt lgkmcnt(0)
	s_setprio 1
	s_waitcnt lgkmcnt(0)
	v_mfma_f32_16x16x32_bf16 v[62:65], v[130:133], v[146:149], v[62:65]
	v_mfma_f32_16x16x32_bf16 v[58:61], v[138:141], v[146:149], v[58:61]
	v_mfma_f32_16x16x32_bf16 v[54:57], v[130:133], v[154:157], v[54:57]
	v_mfma_f32_16x16x32_bf16 v[50:53], v[138:141], v[154:157], v[50:53]
	v_mfma_f32_16x16x32_bf16 v[42:45], v[130:133], v[176:179], v[42:45]
	v_mfma_f32_16x16x32_bf16 v[34:37], v[138:141], v[176:179], v[34:37]
	v_mfma_f32_16x16x32_bf16 v[26:29], v[130:133], v[184:187], v[26:29]
	v_mfma_f32_16x16x32_bf16 v[18:21], v[138:141], v[184:187], v[18:21]
	v_mfma_f32_16x16x32_bf16 v[62:65], v[134:137], v[150:153], v[62:65]
	v_mfma_f32_16x16x32_bf16 v[58:61], v[142:145], v[150:153], v[58:61]
	v_mfma_f32_16x16x32_bf16 v[54:57], v[134:137], v[158:161], v[54:57]
	v_mfma_f32_16x16x32_bf16 v[50:53], v[142:145], v[158:161], v[50:53]
	v_mfma_f32_16x16x32_bf16 v[42:45], v[134:137], v[180:183], v[42:45]
	v_mfma_f32_16x16x32_bf16 v[34:37], v[142:145], v[180:183], v[34:37]
	v_mfma_f32_16x16x32_bf16 v[26:29], v[134:137], v[188:191], v[26:29]
	v_mfma_f32_16x16x32_bf16 v[18:21], v[142:145], v[188:191], v[18:21]
	s_setprio 0
	s_barrier
	s_add_u32 s50, s50, 0x80080
	s_addc_u32 s51, s51, 0
	s_add_i32 s52, s52, s56
	s_mov_b32 m0, s52
	s_nop 0
	global_load_lds_dwordx4 v162, s[50:51]
	s_add_i32 m0, s52, 0x2000
	s_nop 0
	global_load_lds_dwordx4 v164, s[50:51]
	s_waitcnt vmcnt(6)
	s_barrier
	s_setprio 1
	v_mfma_f32_16x16x32_bf16 v[46:49], v[192:195], v[146:149], v[46:49]
	v_mfma_f32_16x16x32_bf16 v[38:41], v[200:203], v[146:149], v[38:41]
	v_mfma_f32_16x16x32_bf16 v[30:33], v[192:195], v[154:157], v[30:33]
	v_mfma_f32_16x16x32_bf16 v[22:25], v[200:203], v[154:157], v[22:25]
	v_mfma_f32_16x16x32_bf16 v[14:17], v[192:195], v[176:179], v[14:17]
	v_mfma_f32_16x16x32_bf16 v[10:13], v[200:203], v[176:179], v[10:13]
	v_mfma_f32_16x16x32_bf16 v[6:9], v[192:195], v[184:187], v[6:9]
	v_mfma_f32_16x16x32_bf16 v[2:5], v[200:203], v[184:187], v[2:5]
	v_mfma_f32_16x16x32_bf16 v[46:49], v[196:199], v[150:153], v[46:49]
	v_mfma_f32_16x16x32_bf16 v[38:41], v[204:207], v[150:153], v[38:41]
	v_mfma_f32_16x16x32_bf16 v[30:33], v[196:199], v[158:161], v[30:33]
	v_mfma_f32_16x16x32_bf16 v[22:25], v[204:207], v[158:161], v[22:25]
	v_mfma_f32_16x16x32_bf16 v[14:17], v[196:199], v[180:183], v[14:17]
	v_mfma_f32_16x16x32_bf16 v[10:13], v[204:207], v[180:183], v[10:13]
	v_mfma_f32_16x16x32_bf16 v[6:9], v[196:199], v[188:191], v[6:9]
	v_mfma_f32_16x16x32_bf16 v[2:5], v[204:207], v[188:191], v[2:5]
	s_setprio 0
	s_add_i32 s80, s80, 2
	s_add_u32 s48, s48, 0x100
	s_addc_u32 s49, s49, 0
	s_add_u32 s74, s74, 0x100
	s_addc_u32 s75, s75, 0
	s_cmp_gt_u32 s80, s87
	s_barrier
	s_cbranch_scc0 .LBB0_1098
